# M3 dno units: the four output-norm weight pieces ride in the unit's first load batch (registers free in this phase), kernarg pointer fetched once per phase; no loads or waits left in the epilogue
# speedup vs baseline: 1.0085x; 1.0010x over previous
.LBB0_906:
	s_cmp_lt_i32 s88, 5
	s_cselect_b64 s[0:1], -1, 0
	s_cmp_gt_i32 s89, 4
	s_cselect_b64 s[2:3], -1, 0
	s_and_b64 s[0:1], s[0:1], s[2:3]
	s_andn2_b64 vcc, exec, s[0:1]
	s_cbranch_vccnz .LBB0_979
	v_readlane_b32 s0, v254, 0
	v_mbcnt_lo_u32_b32 v0, -1, 0
	s_andn2_b32 s0, s0, 63
	v_mbcnt_hi_u32_b32 v32, -1, v0
	v_or_b32_e32 v30, s0, v32
	s_mov_b32 s22, s90
	v_readlane_b32 s2, v254, 3
	s_mov_b64 s[0:1], s[92:93]
	v_readlane_b32 s23, v254, 4
	v_mov_b32_e32 v31, 0
	s_load_dwordx2 s[4:5], s[0:1], 0xe8
	s_load_dwordx2 s[38:39], s[0:1], 0x68
	s_mov_b32 s7, 0
	v_mov_b32_e32 v25, 0
	s_cmpk_gt_i32 s23, 0x3ff
	v_xor_b32_e32 v34, 16, v32
	v_and_b32_e32 v35, 64, v32
	v_xor_b32_e32 v33, 32, v32
	s_cbranch_scc1 .LBB0_920
	s_waitcnt lgkmcnt(0)
	s_add_u32 s24, s4, 0x10000000
	s_addc_u32 s25, s5, 0
	v_add_u32_e32 v0, 64, v35
	s_add_u32 s26, s4, 0x16100000
	v_cmp_lt_i32_e32 vcc, v34, v0
	s_addc_u32 s27, s5, 0
	s_add_u32 s8, s4, 0xb00000
	v_cndmask_b32_e32 v1, v32, v34, vcc
	v_cmp_lt_i32_e32 vcc, v33, v0
	s_addc_u32 s9, s5, 0
	v_lshlrev_b32_e32 v36, 2, v1
	v_cndmask_b32_e32 v0, v32, v33, vcc
	v_lshlrev_b32_e32 v37, 2, v0
	s_mov_b64 s[10:11], 0x10000
	s_mov_b64 s[12:13], 0x10400
	s_mov_b64 s[14:15], 0x14000
	s_movk_i32 s28, 0x1c00
	v_mov_b64_e32 v[26:27], s[4:5]
	s_mov_b64 s[16:17], 0x2e00c00
	s_mov_b32 s29, 0x2e00000
	s_mov_b32 s30, 0xc000
	v_mov_b32_e32 v38, 0x358637bd
	s_mov_b32 s31, 0x800000
	s_mov_b32 s33, s23
	s_branch .LBB0_910

.LBB0_916:
	s_or_b64 exec, exec, s[20:21]
	s_ashr_i32 s19, s18, 31
	s_lshl_b64 s[2:3], s[18:19], 15
	s_add_u32 s2, s26, s2
	s_addc_u32 s3, s27, s3
	v_lshlrev_b32_e32 v1, 1, v13
	v_and_b32_e32 v2, 3, v0
	s_lshl_b32 s6, s35, 5
	v_and_b32_e32 v3, 8, v0
	v_lshrrev_b32_e32 v15, 5, v39
	v_or3_b32 v3, s6, v3, v15
	v_and_b32_e32 v15, 16, v0
	v_and_or_b32 v1, v1, 8, v2
	v_lshl_or_b32 v1, v1, 5, v15
	v_lshlrev_b32_e32 v15, 9, v3
	v_or_b32_e32 v2, v15, v1
	v_ashrrev_i32_e32 v3, 31, v2
	v_lshl_add_u64 v[18:19], s[2:3], 0, v[2:3]
	v_or_b32_e32 v17, 0x2000, v15
	global_load_dwordx4 v[42:45], v[18:19], off
	v_or_b32_e32 v18, v17, v1
	v_ashrrev_i32_e32 v19, 31, v18
	v_or_b32_e32 v22, 0x80, v1
	v_lshl_add_u64 v[18:19], s[2:3], 0, v[18:19]
	global_load_dwordx4 v[50:53], v[18:19], off
	v_or_b32_e32 v18, v17, v22
	v_ashrrev_i32_e32 v19, 31, v18
	v_lshl_add_u64 v[18:19], s[2:3], 0, v[18:19]
	v_ashrrev_i32_e32 v3, 31, v15
	global_load_dwordx4 v[54:57], v[18:19], off
	v_or_b32_e32 v18, v15, v22
	s_nop 0
	v_lshl_add_u64 v[2:3], s[2:3], 0, v[2:3]
	v_ashrrev_i32_e32 v19, 31, v18
	v_or_b32_e32 v114, 0x2400, v15
	global_load_dwordx4 v[46:49], v[2:3], off offset:128
	global_load_dwordx4 v[58:61], v[2:3], off offset:1024
	v_lshl_add_u64 v[20:21], s[2:3], 0, v[18:19]
	v_or_b32_e32 v18, v114, v1
	v_ashrrev_i32_e32 v19, 31, v18
	v_lshl_add_u64 v[18:19], s[2:3], 0, v[18:19]
	global_load_dwordx4 v[62:65], v[2:3], off offset:3072
	global_load_dwordx4 v[66:69], v[20:21], off offset:1024
	global_load_dwordx4 v[70:73], v[18:19], off
	global_load_dwordx4 v[78:81], v[2:3], off offset:2048
	v_or_b32_e32 v18, v114, v22
	v_ashrrev_i32_e32 v19, 31, v18
	v_lshl_add_u64 v[18:19], s[2:3], 0, v[18:19]
	global_load_dwordx4 v[74:77], v[18:19], off
	global_load_dwordx4 v[94:97], v[20:21], off offset:3072
	v_or_b32_e32 v115, 0x2800, v15
	v_or_b32_e32 v2, v115, v1
	global_load_dwordx4 v[82:85], v[20:21], off offset:2048
	v_ashrrev_i32_e32 v3, 31, v2
	v_lshl_add_u64 v[2:3], s[2:3], 0, v[2:3]
	global_load_dwordx4 v[86:89], v[2:3], off
	v_or_b32_e32 v2, v115, v22
	v_or_b32_e32 v115, 0x2c00, v15
	v_or_b32_e32 v20, v115, v1
	v_ashrrev_i32_e32 v3, 31, v2
	v_ashrrev_i32_e32 v21, 31, v20
	v_lshl_add_u64 v[2:3], s[2:3], 0, v[2:3]
	v_lshl_add_u64 v[20:21], s[2:3], 0, v[20:21]
	global_load_dwordx4 v[90:93], v[2:3], off
	global_load_dwordx4 v[98:101], v[20:21], off
	v_or_b32_e32 v20, v115, v22
	v_ashrrev_i32_e32 v21, 31, v20
	v_lshl_add_u64 v[20:21], s[2:3], 0, v[20:21]
	global_load_dwordx4 v[102:105], v[20:21], off
	v_mad_i64_i32 v[2:3], s[18:19], v28, s28, v[26:27]
	s_lshl_b32 s6, s34, 8
	s_lshl_b32 s18, s35, 6
	v_lshrrev_b32_e32 v0, 1, v0
	v_lshl_add_u64 v[2:3], v[2:3], 0, s[6:7]
	s_ashr_i32 s19, s18, 31
	v_and_b32_e32 v41, 24, v0
	v_lshl_add_u64 v[2:3], s[18:19], 1, v[2:3]
	v_lshlrev_b32_e32 v24, 1, v41
	v_lshl_add_u64 v[0:1], v[2:3], 0, v[24:25]
	v_add_co_u32_e64 v108, s[2:3], s29, v0
	v_lshl_add_u64 v[106:107], v[0:1], 0, s[16:17]
	s_nop 0
	v_addc_co_u32_e64 v109, s[2:3], 0, v1, s[2:3]
	v_or_b32_e32 v140, s18, v41
	v_lshlrev_b32_e32 v140, 2, v140
	global_load_dwordx4 v[124:127], v140, s[38:39] offset:0
	global_load_dwordx4 v[128:131], v140, s[38:39] offset:16
	global_load_dwordx4 v[132:135], v140, s[38:39] offset:128
	global_load_dwordx4 v[136:139], v140, s[38:39] offset:144
	global_load_dwordx4 v[20:23], v[108:109], off offset:3072
	global_load_dwordx4 v[0:3], v[106:107], off offset:64
	v_lshlrev_b32_e32 v115, 4, v13
	v_and_b32_e32 v13, 0x70, v115
	v_add_u32_e32 v24, v31, v14
	s_waitcnt vmcnt(0) lgkmcnt(0)
	s_barrier
	v_lshlrev_b32_e32 v16, 16, v8
	v_and_b32_e32 v17, 0xffff0000, v8
	v_lshlrev_b32_e32 v18, 16, v9
	v_and_b32_e32 v19, 0xffff0000, v9
	v_lshlrev_b32_e32 v8, 16, v10
	v_and_b32_e32 v9, 0xffff0000, v10
	v_xad_u32 v10, v13, v12, v24
	ds_read_b128 v[106:109], v10 offset:32768
	v_or_b32_e32 v14, 64, v12
	v_xad_u32 v14, v13, v14, v24
	ds_read_b128 v[110:113], v14 offset:32768
	s_waitcnt lgkmcnt(0)
	v_mfma_f32_16x16x32_bf16 v[14:17], v[42:45], v[106:109], v[16:19]
	v_lshlrev_b32_e32 v10, 16, v11
	v_and_b32_e32 v11, 0xffff0000, v11
	s_nop 0
	v_or_b32_e32 v18, 0x80, v12
	v_xad_u32 v18, v13, v18, v24
	s_waitcnt vmcnt(14)
	v_mfma_f32_16x16x32_bf16 v[8:11], v[46:49], v[106:109], v[8:11]
	v_lshlrev_b32_e32 v42, 16, v4
	v_and_b32_e32 v43, 0xffff0000, v4
	v_lshlrev_b32_e32 v44, 16, v5
	v_and_b32_e32 v45, 0xffff0000, v5
	ds_read_b128 v[46:49], v18 offset:32768
	s_waitcnt vmcnt(13)
	v_mfma_f32_16x16x32_bf16 v[14:17], v[58:61], v[110:113], v[14:17]
	v_or_b32_e32 v12, 0xc0, v12
	v_xad_u32 v12, v13, v12, v24
	v_lshlrev_b32_e32 v4, 16, v6
	v_mfma_f32_16x16x32_bf16 v[42:45], v[50:53], v[106:109], v[42:45]
	v_and_b32_e32 v5, 0xffff0000, v6
	v_lshlrev_b32_e32 v6, 16, v7
	v_and_b32_e32 v7, 0xffff0000, v7
	s_waitcnt vmcnt(11)
	v_mfma_f32_16x16x32_bf16 v[8:11], v[66:69], v[110:113], v[8:11]
	ds_read_b128 v[50:53], v12 offset:32768
	v_cmp_gt_u32_e64 s[2:3], 16, v39
	v_mfma_f32_16x16x32_bf16 v[4:7], v[54:57], v[106:109], v[4:7]
	s_waitcnt vmcnt(10)
	v_mfma_f32_16x16x32_bf16 v[42:45], v[70:73], v[110:113], v[42:45]
	s_waitcnt vmcnt(9) lgkmcnt(1)
	v_mfma_f32_16x16x32_bf16 v[12:15], v[78:81], v[46:49], v[14:17]
	s_waitcnt vmcnt(6)
	v_mfma_f32_16x16x32_bf16 v[8:11], v[82:85], v[46:49], v[8:11]
	v_mfma_f32_16x16x32_bf16 v[4:7], v[74:77], v[110:113], v[4:7]
	s_waitcnt vmcnt(5)
	v_mfma_f32_16x16x32_bf16 v[42:45], v[86:89], v[46:49], v[42:45]
	s_waitcnt lgkmcnt(0)
	v_mfma_f32_16x16x32_bf16 v[16:19], v[62:65], v[50:53], v[12:15]
	v_mfma_f32_16x16x32_bf16 v[12:15], v[94:97], v[50:53], v[8:11]
	s_waitcnt vmcnt(4)
	v_mfma_f32_16x16x32_bf16 v[4:7], v[90:93], v[46:49], v[4:7]
	s_nop 4
	v_mul_f32_e32 v24, v17, v17
	v_fmac_f32_e32 v24, v16, v16
	s_waitcnt vmcnt(3)
	v_mfma_f32_16x16x32_bf16 v[8:11], v[98:101], v[50:53], v[42:45]
	s_nop 2
	v_mul_f32_e32 v42, v19, v19
	v_fmac_f32_e32 v42, v18, v18
	v_add_f32_e32 v24, v24, v42
	v_mul_f32_e32 v42, v13, v13
	v_mul_f32_e32 v43, v15, v15
	v_fmac_f32_e32 v42, v12, v12
	v_fmac_f32_e32 v43, v14, v14
	s_waitcnt vmcnt(2)
	v_mfma_f32_16x16x32_bf16 v[4:7], v[102:105], v[50:53], v[4:7]
	v_add_f32_e32 v42, v42, v43
	v_add_f32_e32 v24, v24, v42
	v_mul_f32_e32 v42, v9, v9
	v_mul_f32_e32 v43, v11, v11
	v_fmac_f32_e32 v42, v8, v8
	v_fmac_f32_e32 v43, v10, v10
	v_add_f32_e32 v42, v42, v43
	v_add_f32_e32 v24, v24, v42
	v_mul_f32_e32 v42, v5, v5
	v_mul_f32_e32 v43, v7, v7
	v_fmac_f32_e32 v42, v4, v4
	v_fmac_f32_e32 v43, v6, v6
	v_add_f32_e32 v42, v42, v43
	v_add_f32_e32 v24, v24, v42
	ds_bpermute_b32 v42, v36, v24
	s_waitcnt lgkmcnt(0)
	v_add_f32_e32 v42, v24, v42
	ds_bpermute_b32 v43, v37, v42
	v_lshlrev_b32_e32 v24, 3, v40
	s_and_saveexec_b64 s[20:21], s[2:3]
	s_cbranch_execz .LBB0_918
	s_lshl_b32 s2, s35, 2
	v_add3_u32 v39, v31, v24, s2
	s_waitcnt lgkmcnt(0)
	v_add_f32_e32 v40, v42, v43
	ds_write_b32 v39, v40 offset:49152
.LBB0_918:
	s_or_b64 exec, exec, s[20:21]
	s_waitcnt lgkmcnt(0)
	s_barrier
	s_and_saveexec_b64 s[2:3], vcc
	s_cbranch_execz .LBB0_909
	s_nop 0
	s_nop 0
	s_nop 0
	s_nop 0
	s_nop 0
	v_or_b32_e32 v48, s18, v41
	v_ashrrev_i32_e32 v49, 31, v48
	v_add3_u32 v24, v31, v24, s30
	s_waitcnt vmcnt(1)
	v_lshlrev_b32_e32 v52, 16, v20
	v_and_b32_e32 v53, 0xffff0000, v20
	v_lshlrev_b32_e32 v20, 16, v21
	v_lshlrev_b32_e32 v54, 16, v22
	v_and_b32_e32 v55, 0xffff0000, v22
	v_lshlrev_b32_e32 v22, 16, v23
	ds_read2_b32 v[56:57], v24 offset1:1
	v_mul_f32_e32 v24, 0xbfb8aa3b, v52
	v_mul_f32_e32 v58, 0xbfb8aa3b, v20
	v_mul_f32_e32 v60, 0xbfb8aa3b, v54
	v_mul_f32_e32 v62, 0xbfb8aa3b, v22
	s_lshl_b32 s6, s34, 7
	v_lshlrev_b64 v[28:29], 11, v[28:29]
	v_exp_f32_e32 v24, v24
	v_exp_f32_e32 v58, v58
	v_exp_f32_e32 v60, v60
	v_exp_f32_e32 v62, v62
	v_lshl_add_u64 v[28:29], s[8:9], 0, v[28:29]
	s_lshl_b32 s6, s6, 1
	v_lshl_add_u64 v[28:29], v[28:29], 0, s[6:7]
	v_and_b32_e32 v21, 0xffff0000, v21
	v_and_b32_e32 v23, 0xffff0000, v23
	v_lshl_add_u64 v[28:29], v[48:49], 1, v[28:29]
	s_waitcnt lgkmcnt(0)
	v_add_f32_e32 v48, v56, v57
	v_mul_f32_e32 v39, 0xbfb8aa3b, v53
	v_mul_f32_e32 v59, 0xbfb8aa3b, v21
	v_mul_f32_e32 v61, 0xbfb8aa3b, v55
	v_mul_f32_e32 v63, 0xbfb8aa3b, v23
	v_add_f32_e32 v24, 1.0, v24
	v_add_f32_e32 v56, 1.0, v58
	v_add_f32_e32 v58, 1.0, v60
	v_add_f32_e32 v60, 1.0, v62
	v_fmamk_f32 v62, v48, 0x3c000000, v38
	v_exp_f32_e32 v39, v39
	v_exp_f32_e32 v59, v59
	v_exp_f32_e32 v61, v61
	v_exp_f32_e32 v63, v63
	v_rcp_f32_e32 v48, v24
	v_mul_f32_e32 v24, 0x4b800000, v62
	v_cmp_gt_f32_e32 vcc, s31, v62
	v_add_f32_e32 v39, 1.0, v39
	v_add_f32_e32 v57, 1.0, v59
	v_cndmask_b32_e32 v24, v62, v24, vcc
	v_rsq_f32_e32 v24, v24
	v_add_f32_e32 v59, 1.0, v61
	v_add_f32_e32 v61, 1.0, v63
	v_rcp_f32_e32 v49, v39
	v_rcp_f32_e32 v56, v56
	v_rcp_f32_e32 v57, v57
	v_rcp_f32_e32 v58, v58
	v_rcp_f32_e32 v59, v59
	v_rcp_f32_e32 v60, v60
	v_rcp_f32_e32 v61, v61
	v_mul_f32_e32 v39, 0x45800000, v24
	v_cndmask_b32_e32 v24, v24, v39, vcc
	v_pk_mul_f32 v[16:17], v[16:17], v[24:25] op_sel_hi:[1,0]
	v_pk_mul_f32 v[18:19], v[18:19], v[24:25] op_sel_hi:[1,0]
	v_pk_mul_f32 v[12:13], v[12:13], v[24:25] op_sel_hi:[1,0]
	v_pk_mul_f32 v[14:15], v[14:15], v[24:25] op_sel_hi:[1,0]
	v_pk_mul_f32 v[48:49], v[48:49], v[52:53]
	v_pk_mul_f32 v[20:21], v[56:57], v[20:21]
	v_pk_mul_f32 v[52:53], v[58:59], v[54:55]
	v_pk_mul_f32 v[22:23], v[60:61], v[22:23]
	v_pk_mul_f32 v[8:9], v[8:9], v[24:25] op_sel_hi:[1,0]
	v_pk_mul_f32 v[10:11], v[10:11], v[24:25] op_sel_hi:[1,0]
	v_pk_mul_f32 v[4:5], v[4:5], v[24:25] op_sel_hi:[1,0]
	v_pk_mul_f32 v[6:7], v[6:7], v[24:25] op_sel_hi:[1,0]
	v_pk_mul_f32 v[16:17], v[124:125], v[16:17]
	v_pk_mul_f32 v[18:19], v[126:127], v[18:19]
	v_pk_mul_f32 v[12:13], v[128:129], v[12:13]
	v_pk_mul_f32 v[14:15], v[130:131], v[14:15]
	v_pk_mul_f32 v[16:17], v[48:49], v[16:17]
	v_pk_mul_f32 v[18:19], v[20:21], v[18:19]
	v_pk_mul_f32 v[20:21], v[52:53], v[12:13]
	v_pk_mul_f32 v[22:23], v[22:23], v[14:15]
	v_cvt_pk_bf16_f32 v12, v16, v17
	v_cvt_pk_bf16_f32 v13, v18, v19
	v_cvt_pk_bf16_f32 v14, v20, v21
	v_cvt_pk_bf16_f32 v15, v22, v23
	global_store_dwordx4 v[28:29], v[12:15], off
	s_nop 0
	v_lshlrev_b32_e32 v20, 16, v0
	v_and_b32_e32 v21, 0xffff0000, v0
	v_lshlrev_b32_e32 v0, 16, v1
	v_and_b32_e32 v1, 0xffff0000, v1
	v_lshlrev_b32_e32 v22, 16, v2
	v_and_b32_e32 v23, 0xffff0000, v2
	v_lshlrev_b32_e32 v2, 16, v3
	v_and_b32_e32 v3, 0xffff0000, v3
	v_mul_f32_e32 v39, 0xbfb8aa3b, v20
	v_mul_f32_e32 v40, 0xbfb8aa3b, v21
	v_mul_f32_e32 v41, 0xbfb8aa3b, v0
	v_mul_f32_e32 v42, 0xbfb8aa3b, v1
	v_mul_f32_e32 v43, 0xbfb8aa3b, v22
	v_mul_f32_e32 v44, 0xbfb8aa3b, v23
	v_mul_f32_e32 v45, 0xbfb8aa3b, v2
	v_mul_f32_e32 v46, 0xbfb8aa3b, v3
	v_exp_f32_e32 v39, v39
	v_exp_f32_e32 v40, v40
	v_exp_f32_e32 v41, v41
	v_exp_f32_e32 v42, v42
	v_exp_f32_e32 v43, v43
	v_exp_f32_e32 v44, v44
	v_exp_f32_e32 v45, v45
	v_exp_f32_e32 v46, v46
	v_add_f32_e32 v39, 1.0, v39
	v_add_f32_e32 v47, 1.0, v40
	v_add_f32_e32 v48, 1.0, v41
	v_add_f32_e32 v49, 1.0, v42
	v_add_f32_e32 v50, 1.0, v43
	v_add_f32_e32 v51, 1.0, v44
	v_add_f32_e32 v52, 1.0, v45
	v_add_f32_e32 v53, 1.0, v46
	v_rcp_f32_e32 v40, v39
	v_rcp_f32_e32 v41, v47
	v_rcp_f32_e32 v42, v48
	v_rcp_f32_e32 v43, v49
	v_rcp_f32_e32 v44, v50
	v_rcp_f32_e32 v45, v51
	v_rcp_f32_e32 v46, v52
	v_rcp_f32_e32 v47, v53
	v_pk_mul_f32 v[20:21], v[40:41], v[20:21]
	v_pk_mul_f32 v[0:1], v[42:43], v[0:1]
	v_pk_mul_f32 v[22:23], v[44:45], v[22:23]
	v_pk_mul_f32 v[2:3], v[46:47], v[2:3]
	v_pk_mul_f32 v[8:9], v[132:133], v[8:9]
	v_pk_mul_f32 v[10:11], v[134:135], v[10:11]
	v_pk_mul_f32 v[4:5], v[136:137], v[4:5]
	v_pk_mul_f32 v[6:7], v[138:139], v[6:7]
	v_pk_mul_f32 v[8:9], v[20:21], v[8:9]
	v_pk_mul_f32 v[10:11], v[0:1], v[10:11]
	v_pk_mul_f32 v[4:5], v[22:23], v[4:5]
	v_pk_mul_f32 v[6:7], v[2:3], v[6:7]
	v_cvt_pk_bf16_f32 v0, v8, v9
	v_cvt_pk_bf16_f32 v1, v10, v11
	v_cvt_pk_bf16_f32 v2, v4, v5
	v_cvt_pk_bf16_f32 v3, v6, v7
	global_store_dwordx4 v[28:29], v[0:3], off offset:64
	s_branch .LBB0_909

.LBB0_2415:
	s_cmp_lt_i32 s88, 14
	s_cselect_b64 s[0:1], -1, 0
	s_cmp_gt_i32 s89, 13
	s_cselect_b64 s[2:3], -1, 0
	s_and_b64 s[0:1], s[0:1], s[2:3]
	s_andn2_b64 vcc, exec, s[0:1]
	s_cbranch_vccnz .LBB0_2488
	v_readlane_b32 s0, v254, 0
	s_waitcnt vmcnt(0)
	v_mbcnt_lo_u32_b32 v0, -1, 0
	s_andn2_b32 s0, s0, 63
	v_mbcnt_hi_u32_b32 v32, -1, v0
	v_or_b32_e32 v30, s0, v32
	v_mov_b32_e32 v31, 0
	s_mov_b32 s22, s90
	v_readlane_b32 s2, v254, 3
	s_mov_b64 s[0:1], s[92:93]
	v_readlane_b32 s23, v254, 4
	s_waitcnt lgkmcnt(0)
	s_load_dwordx2 s[4:5], s[0:1], 0xe8
	s_load_dwordx2 s[38:39], s[0:1], 0x68
	s_mov_b32 s7, 0
	v_mov_b32_e32 v25, 0
	s_cmpk_gt_i32 s23, 0x3ff
	v_xor_b32_e32 v34, 16, v32
	v_and_b32_e32 v35, 64, v32
	v_xor_b32_e32 v33, 32, v32
	s_cbranch_scc1 .LBB0_2429
	s_waitcnt lgkmcnt(0)
	s_add_u32 s24, s4, 0x10000000
	s_addc_u32 s25, s5, 0
	v_add_u32_e32 v0, 64, v35
	s_add_u32 s26, s4, 0x16100000
	v_cmp_lt_i32_e32 vcc, v34, v0
	s_addc_u32 s27, s5, 0
	s_add_u32 s8, s4, 0xb00000
	v_cndmask_b32_e32 v1, v32, v34, vcc
	v_cmp_lt_i32_e32 vcc, v33, v0
	s_addc_u32 s9, s5, 0
	v_lshlrev_b32_e32 v36, 2, v1
	v_cndmask_b32_e32 v0, v32, v33, vcc
	v_lshlrev_b32_e32 v37, 2, v0
	s_mov_b64 s[10:11], 0x10000
	s_mov_b64 s[12:13], 0x10400
	s_mov_b64 s[14:15], 0x14000
	s_movk_i32 s28, 0x1c00
	v_mov_b64_e32 v[26:27], s[4:5]
	s_mov_b64 s[16:17], 0x2e00c00
	s_mov_b32 s29, 0x2e00000
	s_mov_b32 s30, 0xc000
	v_mov_b32_e32 v38, 0x358637bd
	s_mov_b32 s31, 0x800000
	s_mov_b32 s33, s23
	s_branch .LBB0_2419

.LBB0_2425:
	s_or_b64 exec, exec, s[20:21]
	s_ashr_i32 s19, s18, 31
	s_lshl_b64 s[2:3], s[18:19], 15
	s_add_u32 s2, s26, s2
	s_addc_u32 s3, s27, s3
	v_lshlrev_b32_e32 v1, 1, v13
	v_and_b32_e32 v2, 3, v0
	s_lshl_b32 s6, s35, 5
	v_and_b32_e32 v3, 8, v0
	v_lshrrev_b32_e32 v15, 5, v39
	v_or3_b32 v3, s6, v3, v15
	v_and_b32_e32 v15, 16, v0
	v_and_or_b32 v1, v1, 8, v2
	v_lshl_or_b32 v1, v1, 5, v15
	v_lshlrev_b32_e32 v15, 9, v3
	v_or_b32_e32 v2, v15, v1
	v_ashrrev_i32_e32 v3, 31, v2
	v_lshl_add_u64 v[18:19], s[2:3], 0, v[2:3]
	v_or_b32_e32 v17, 0x2000, v15
	global_load_dwordx4 v[42:45], v[18:19], off
	v_or_b32_e32 v18, v17, v1
	v_ashrrev_i32_e32 v19, 31, v18
	v_or_b32_e32 v22, 0x80, v1
	v_lshl_add_u64 v[18:19], s[2:3], 0, v[18:19]
	global_load_dwordx4 v[50:53], v[18:19], off
	v_or_b32_e32 v18, v17, v22
	v_ashrrev_i32_e32 v19, 31, v18
	v_lshl_add_u64 v[18:19], s[2:3], 0, v[18:19]
	v_ashrrev_i32_e32 v3, 31, v15
	global_load_dwordx4 v[54:57], v[18:19], off
	v_or_b32_e32 v18, v15, v22
	s_nop 0
	v_lshl_add_u64 v[2:3], s[2:3], 0, v[2:3]
	v_ashrrev_i32_e32 v19, 31, v18
	v_or_b32_e32 v114, 0x2400, v15
	global_load_dwordx4 v[46:49], v[2:3], off offset:128
	global_load_dwordx4 v[58:61], v[2:3], off offset:1024
	v_lshl_add_u64 v[20:21], s[2:3], 0, v[18:19]
	v_or_b32_e32 v18, v114, v1
	v_ashrrev_i32_e32 v19, 31, v18
	v_lshl_add_u64 v[18:19], s[2:3], 0, v[18:19]
	global_load_dwordx4 v[62:65], v[2:3], off offset:3072
	global_load_dwordx4 v[66:69], v[20:21], off offset:1024
	global_load_dwordx4 v[70:73], v[18:19], off
	global_load_dwordx4 v[78:81], v[2:3], off offset:2048
	v_or_b32_e32 v18, v114, v22
	v_ashrrev_i32_e32 v19, 31, v18
	v_lshl_add_u64 v[18:19], s[2:3], 0, v[18:19]
	global_load_dwordx4 v[74:77], v[18:19], off
	global_load_dwordx4 v[94:97], v[20:21], off offset:3072
	v_or_b32_e32 v115, 0x2800, v15
	v_or_b32_e32 v2, v115, v1
	global_load_dwordx4 v[82:85], v[20:21], off offset:2048
	v_ashrrev_i32_e32 v3, 31, v2
	v_lshl_add_u64 v[2:3], s[2:3], 0, v[2:3]
	global_load_dwordx4 v[86:89], v[2:3], off
	v_or_b32_e32 v2, v115, v22
	v_or_b32_e32 v115, 0x2c00, v15
	v_or_b32_e32 v20, v115, v1
	v_ashrrev_i32_e32 v3, 31, v2
	v_ashrrev_i32_e32 v21, 31, v20
	v_lshl_add_u64 v[2:3], s[2:3], 0, v[2:3]
	v_lshl_add_u64 v[20:21], s[2:3], 0, v[20:21]
	global_load_dwordx4 v[90:93], v[2:3], off
	global_load_dwordx4 v[98:101], v[20:21], off
	v_or_b32_e32 v20, v115, v22
	v_ashrrev_i32_e32 v21, 31, v20
	v_lshl_add_u64 v[20:21], s[2:3], 0, v[20:21]
	global_load_dwordx4 v[102:105], v[20:21], off
	v_mad_i64_i32 v[2:3], s[18:19], v28, s28, v[26:27]
	s_lshl_b32 s6, s34, 8
	s_lshl_b32 s18, s35, 6
	v_lshrrev_b32_e32 v0, 1, v0
	v_lshl_add_u64 v[2:3], v[2:3], 0, s[6:7]
	s_ashr_i32 s19, s18, 31
	v_and_b32_e32 v41, 24, v0
	v_lshl_add_u64 v[2:3], s[18:19], 1, v[2:3]
	v_lshlrev_b32_e32 v24, 1, v41
	v_lshl_add_u64 v[0:1], v[2:3], 0, v[24:25]
	v_add_co_u32_e64 v108, s[2:3], s29, v0
	v_lshl_add_u64 v[106:107], v[0:1], 0, s[16:17]
	s_nop 0
	v_addc_co_u32_e64 v109, s[2:3], 0, v1, s[2:3]
	v_or_b32_e32 v140, s18, v41
	v_lshlrev_b32_e32 v140, 2, v140
	global_load_dwordx4 v[124:127], v140, s[38:39] offset:512
	global_load_dwordx4 v[128:131], v140, s[38:39] offset:528
	global_load_dwordx4 v[132:135], v140, s[38:39] offset:640
	global_load_dwordx4 v[136:139], v140, s[38:39] offset:656
	global_load_dwordx4 v[20:23], v[108:109], off offset:3072
	global_load_dwordx4 v[0:3], v[106:107], off offset:64
	v_lshlrev_b32_e32 v115, 4, v13
	v_and_b32_e32 v13, 0x70, v115
	v_add_u32_e32 v24, v31, v14
	s_waitcnt vmcnt(0) lgkmcnt(0)
	s_barrier
	v_lshlrev_b32_e32 v16, 16, v8
	v_and_b32_e32 v17, 0xffff0000, v8
	v_lshlrev_b32_e32 v18, 16, v9
	v_and_b32_e32 v19, 0xffff0000, v9
	v_lshlrev_b32_e32 v8, 16, v10
	v_and_b32_e32 v9, 0xffff0000, v10
	v_xad_u32 v10, v13, v12, v24
	ds_read_b128 v[106:109], v10 offset:32768
	v_or_b32_e32 v14, 64, v12
	v_xad_u32 v14, v13, v14, v24
	ds_read_b128 v[110:113], v14 offset:32768
	s_waitcnt lgkmcnt(0)
	v_mfma_f32_16x16x32_bf16 v[14:17], v[42:45], v[106:109], v[16:19]
	v_lshlrev_b32_e32 v10, 16, v11
	v_and_b32_e32 v11, 0xffff0000, v11
	s_nop 0
	v_or_b32_e32 v18, 0x80, v12
	v_xad_u32 v18, v13, v18, v24
	s_waitcnt vmcnt(14)
	v_mfma_f32_16x16x32_bf16 v[8:11], v[46:49], v[106:109], v[8:11]
	v_lshlrev_b32_e32 v42, 16, v4
	v_and_b32_e32 v43, 0xffff0000, v4
	v_lshlrev_b32_e32 v44, 16, v5
	v_and_b32_e32 v45, 0xffff0000, v5
	ds_read_b128 v[46:49], v18 offset:32768
	s_waitcnt vmcnt(13)
	v_mfma_f32_16x16x32_bf16 v[14:17], v[58:61], v[110:113], v[14:17]
	v_or_b32_e32 v12, 0xc0, v12
	v_xad_u32 v12, v13, v12, v24
	v_lshlrev_b32_e32 v4, 16, v6
	v_mfma_f32_16x16x32_bf16 v[42:45], v[50:53], v[106:109], v[42:45]
	v_and_b32_e32 v5, 0xffff0000, v6
	v_lshlrev_b32_e32 v6, 16, v7
	v_and_b32_e32 v7, 0xffff0000, v7
	s_waitcnt vmcnt(11)
	v_mfma_f32_16x16x32_bf16 v[8:11], v[66:69], v[110:113], v[8:11]
	ds_read_b128 v[50:53], v12 offset:32768
	v_cmp_gt_u32_e64 s[2:3], 16, v39
	v_mfma_f32_16x16x32_bf16 v[4:7], v[54:57], v[106:109], v[4:7]
	s_waitcnt vmcnt(10)
	v_mfma_f32_16x16x32_bf16 v[42:45], v[70:73], v[110:113], v[42:45]
	s_waitcnt vmcnt(9) lgkmcnt(1)
	v_mfma_f32_16x16x32_bf16 v[12:15], v[78:81], v[46:49], v[14:17]
	s_waitcnt vmcnt(6)
	v_mfma_f32_16x16x32_bf16 v[8:11], v[82:85], v[46:49], v[8:11]
	v_mfma_f32_16x16x32_bf16 v[4:7], v[74:77], v[110:113], v[4:7]
	s_waitcnt vmcnt(5)
	v_mfma_f32_16x16x32_bf16 v[42:45], v[86:89], v[46:49], v[42:45]
	s_waitcnt lgkmcnt(0)
	v_mfma_f32_16x16x32_bf16 v[16:19], v[62:65], v[50:53], v[12:15]
	v_mfma_f32_16x16x32_bf16 v[12:15], v[94:97], v[50:53], v[8:11]
	s_waitcnt vmcnt(4)
	v_mfma_f32_16x16x32_bf16 v[4:7], v[90:93], v[46:49], v[4:7]
	s_nop 4
	v_mul_f32_e32 v24, v17, v17
	v_fmac_f32_e32 v24, v16, v16
	s_waitcnt vmcnt(3)
	v_mfma_f32_16x16x32_bf16 v[8:11], v[98:101], v[50:53], v[42:45]
	s_nop 2
	v_mul_f32_e32 v42, v19, v19
	v_fmac_f32_e32 v42, v18, v18
	v_add_f32_e32 v24, v24, v42
	v_mul_f32_e32 v42, v13, v13
	v_mul_f32_e32 v43, v15, v15
	v_fmac_f32_e32 v42, v12, v12
	v_fmac_f32_e32 v43, v14, v14
	s_waitcnt vmcnt(2)
	v_mfma_f32_16x16x32_bf16 v[4:7], v[102:105], v[50:53], v[4:7]
	v_add_f32_e32 v42, v42, v43
	v_add_f32_e32 v24, v24, v42
	v_mul_f32_e32 v42, v9, v9
	v_mul_f32_e32 v43, v11, v11
	v_fmac_f32_e32 v42, v8, v8
	v_fmac_f32_e32 v43, v10, v10
	v_add_f32_e32 v42, v42, v43
	v_add_f32_e32 v24, v24, v42
	v_mul_f32_e32 v42, v5, v5
	v_mul_f32_e32 v43, v7, v7
	v_fmac_f32_e32 v42, v4, v4
	v_fmac_f32_e32 v43, v6, v6
	v_add_f32_e32 v42, v42, v43
	v_add_f32_e32 v24, v24, v42
	ds_bpermute_b32 v42, v36, v24
	s_waitcnt lgkmcnt(0)
	v_add_f32_e32 v42, v24, v42
	ds_bpermute_b32 v43, v37, v42
	v_lshlrev_b32_e32 v24, 3, v40
	s_and_saveexec_b64 s[20:21], s[2:3]
	s_cbranch_execz .LBB0_2427
	s_lshl_b32 s2, s35, 2
	v_add3_u32 v39, v31, v24, s2
	s_waitcnt lgkmcnt(0)
	v_add_f32_e32 v40, v42, v43
	ds_write_b32 v39, v40 offset:49152
